# P9 row loop software-pipelined like P6/P11 (next row's x1/ffn/p loads issued at the top of the current row, handed over at the back-edge after a counted wait)
# speedup vs baseline: 1.0056x; 1.0023x over previous
; __device__ __forceinline__ unsigned pk2(float lo, float hi) { return f2bf(lo) | (f2bf(hi) << 16); }
; __global__ void __launch_bounds__(NWAVES * 64, 2) hymba_fwd(Args args) {
;     ...
;         f32x4 g1[4];
; #pragma unroll
;         for (int j = 0; j < 4; ++j) g1[j] = *(const f32x4*)(args.in[23] + 4 * lane + 256 * j);
;         for (int m = gw; m < MROWS; m += NGW) { const v2u* xr = (const v2u*)(X1B + (size_t)m * DM) + lane; const v2u* mr = (const v2u*)(H + (size_t)m * DM) + lane;
;             f32x4 v[4], mx[4]; float s = 0.f;
; #pragma unroll
;             for (int j = 0; j < 4; ++j) { { const v2u wx = __builtin_nontemporal_load(xr + 64 * j); v[j] = (f32x4){bflo(wx.x), bfhi(wx.x), bflo(wx.y), bfhi(wx.y)}; } const v2u w = __builtin_nontemporal_load(mr + 64 * j); mx[j] = (f32x4){bflo(w.x), bfhi(w.x), bflo(w.y), bfhi(w.y)};
;               s += (mx[j].x * mx[j].x + mx[j].y * mx[j].y) + (mx[j].z * mx[j].z + mx[j].w * mx[j].w); }
;             const float rs = 1.0f / sqrtf(wave_sum(s) * (1.0f / DM) + EPS);
;             v2u* o8 = (v2u*)(X2B + (size_t)m * DM) + lane;
; #pragma unroll
;             for (int j = 0; j < 4; ++j) { v[j] = v[j] + mx[j] * rs * g1[j]; v2u w; w.x = pk2(v[j].x, v[j].y); w.y = pk2(v[j].z, v[j].w); o8[64 * j] = w; }
;             const f32x4 pv = __builtin_nontemporal_load((const f32x4*)prow_ptr(args, m) + lane); v2u w; w.x = pk2(pv.x, pv.y); w.y = pk2(pv.z, pv.w); *((v2u*)(PB + (size_t)m * 256) + lane) = w; }
.LBB0_822:
	s_cmp_lt_i32 s14, 0xc000
	s_cbranch_scc0 .LBB0_825
	v_lshlrev_b32_e32 v17, 4, v18
	global_load_dwordx4 v[0:3], v17, s[66:67]
	global_load_dwordx4 v[4:7], v17, s[66:67] offset:1024
	global_load_dwordx4 v[8:11], v17, s[66:67] offset:2048
	global_load_dwordx4 v[12:15], v17, s[66:67] offset:3072
	s_ashr_i32 s0, s3, 31
	s_ashr_i32 s1, s60, 31
	s_add_u32 s10, s3, s60
	s_addc_u32 s11, s0, s1
	s_ashr_i32 s35, s34, 31
	s_lshl_b64 s[0:1], s[10:11], 9
	s_add_u32 s0, s70, s0
	s_addc_u32 s1, s71, s1
	s_add_u32 s12, s0, 0xdf00000
	s_addc_u32 s13, s1, 0
	s_lshl_b64 s[14:15], s[34:35], 9
	s_lshl_b64 s[0:1], s[10:11], 11
	s_add_u32 s16, s68, s0
	s_addc_u32 s17, s69, s1
	s_lshl_b64 s[18:19], s[34:35], 11
	s_add_u32 s20, s70, s0
	v_mov_b32_e32 v17, 0
	s_addc_u32 s21, s71, s1
	s_mov_b32 s3, 0xffff0000
	v_mov_b32_e32 v19, 0x358637bd
	v_mov_b32_e32 v20, 0x3a800000
	s_mov_b32 s26, 0xf800000
	v_mov_b32_e32 v21, 0x260
	s_movk_i32 s27, 0x7fff
	s_mov_b32 s28, 0x7f00000
	v_lshlrev_b32_e32 v18, 4, v18
	v_lshl_add_u64 v[126:127], s[16:17], 0, v[16:17]
	global_load_dwordx2 v[28:29], v[126:127], off nt
	global_load_dwordx2 v[30:31], v[126:127], off offset:512 nt
	global_load_dwordx2 v[32:33], v[126:127], off offset:1024 nt
	global_load_dwordx2 v[34:35], v[126:127], off offset:1536 nt
	v_lshl_add_u64 v[126:127], s[20:21], 0, v[16:17]
	v_add_co_u32_e32 v126, vcc, 0x1900000, v126
	s_nop 1
	v_addc_co_u32_e32 v127, vcc, 0, v127, vcc
	global_load_dwordx2 v[24:25], v[126:127], off nt
	global_load_dwordx2 v[36:37], v[126:127], off offset:512 nt
	global_load_dwordx2 v[38:39], v[126:127], off offset:1024 nt
	global_load_dwordx2 v[26:27], v[126:127], off offset:1536 nt
	s_add_i32 s100, s10, 0xffff8000
	s_cmp_lt_i32 s10, 0x8000
	s_cselect_b32 s101, s11, 0
	s_cselect_b32 s100, s10, s100
	s_cselect_b32 s99, s41, s43
	s_cselect_b32 s98, s40, s42
	s_lshl_b64 s[100:101], s[100:101], 10
	s_add_u32 s98, s98, s100
	s_addc_u32 s99, s99, s101
	global_load_dwordx4 v[100:103], v18, s[98:99] nt
	s_waitcnt vmcnt(0)
.LBB0_824:
	v_lshl_add_u64 v[124:125], s[20:21], 0, v[16:17]
	v_add_co_u32_e64 v22, s[0:1], s28, v124
	s_nop 1
	v_addc_co_u32_e64 v23, s[0:1], 0, v125, s[0:1]
	s_add_u32 s98, s10, s34
	s_addc_u32 s99, s11, s35
	s_cmp_gt_i32 s98, 0xbfff
	s_cbranch_scc1 .Lp9_nopf
	s_add_u32 s100, s16, s18
	s_addc_u32 s101, s17, s19
	s_add_u32 s24, s20, s18
	s_addc_u32 s25, s21, s19
	v_lshl_add_u64 v[126:127], s[100:101], 0, v[16:17]
	global_load_dwordx2 v[104:105], v[126:127], off nt
	global_load_dwordx2 v[106:107], v[126:127], off offset:512 nt
	global_load_dwordx2 v[108:109], v[126:127], off offset:1024 nt
	global_load_dwordx2 v[110:111], v[126:127], off offset:1536 nt
	v_lshl_add_u64 v[126:127], s[24:25], 0, v[16:17]
	v_add_co_u32_e32 v126, vcc, 0x1900000, v126
	s_nop 1
	v_addc_co_u32_e32 v127, vcc, 0, v127, vcc
	global_load_dwordx2 v[112:113], v[126:127], off nt
	global_load_dwordx2 v[114:115], v[126:127], off offset:512 nt
	global_load_dwordx2 v[116:117], v[126:127], off offset:1024 nt
	global_load_dwordx2 v[118:119], v[126:127], off offset:1536 nt
	s_add_i32 s100, s98, 0xffff8000
	s_cmp_lt_i32 s98, 0x8000
	s_cselect_b32 s101, s99, 0
	s_cselect_b32 s100, s98, s100
	s_cselect_b32 s99, s41, s43
	s_cselect_b32 s98, s40, s42
	s_lshl_b64 s[100:101], s[100:101], 10
	s_add_u32 s98, s98, s100
	s_addc_u32 s99, s99, s101
	global_load_dwordx4 v[120:123], v18, s[98:99] nt
.Lp9_nopf:
	v_mov_b32_e32 v56, 0
	v_mov_b32_e32 v57, 0
	s_add_u32 s10, s10, s34
	s_addc_u32 s11, s11, s35
	v_lshlrev_b32_e32 v40, 16, v28
	v_and_b32_e32 v41, 0xffff0000, v28
	v_lshlrev_b32_e32 v28, 16, v29
	v_and_b32_e32 v29, 0xffff0000, v29
	v_lshlrev_b32_e32 v42, 16, v30
	v_and_b32_e32 v43, 0xffff0000, v30
	v_lshlrev_b32_e32 v30, 16, v31
	v_lshlrev_b32_e32 v48, 16, v24
	v_and_b32_e32 v49, 0xffff0000, v24
	v_lshlrev_b32_e32 v24, 16, v25
	v_and_b32_e32 v25, 0xffff0000, v25
	v_lshlrev_b32_e32 v50, 16, v36
	v_and_b32_e32 v51, 0xffff0000, v36
	v_lshlrev_b32_e32 v36, 16, v37
	v_and_b32_e32 v37, 0xffff0000, v37
	v_lshlrev_b32_e32 v52, 16, v38
	v_and_b32_e32 v53, 0xffff0000, v38
	v_lshlrev_b32_e32 v38, 16, v39
	v_and_b32_e32 v39, 0xffff0000, v39
	v_mul_f32_e32 v58, v49, v49
	v_mul_f32_e32 v59, v25, v25
	v_mul_f32_e32 v60, v51, v51
	v_mul_f32_e32 v61, v37, v37
	v_lshlrev_b32_e32 v54, 16, v26
	v_and_b32_e32 v55, 0xffff0000, v26
	v_lshlrev_b32_e32 v26, 16, v27
	v_and_b32_e32 v27, 0xffff0000, v27
	v_mul_f32_e32 v62, v53, v53
	v_mul_f32_e32 v63, v39, v39
	v_fmac_f32_e32 v58, v48, v48
	v_fmac_f32_e32 v59, v24, v24
	v_fmac_f32_e32 v60, v50, v50
	v_fmac_f32_e32 v61, v36, v36
	v_mul_f32_e32 v64, v55, v55
	v_mul_f32_e32 v65, v27, v27
	v_fmac_f32_e32 v62, v52, v52
	v_fmac_f32_e32 v63, v38, v38
	v_add_f32_e32 v58, v58, v59
	v_add_f32_e32 v59, v60, v61
	v_fmac_f32_e32 v64, v54, v54
	v_fmac_f32_e32 v65, v26, v26
	v_add_f32_e32 v60, v62, v63
	v_add_f32_e32 v58, v58, v59
	v_add_f32_e32 v61, v64, v65
	v_add_f32_e32 v58, v58, v60
	v_add_f32_e32 v58, v58, v61
	v_and_b32_e32 v31, 0xffff0000, v31
	v_lshlrev_b32_e32 v44, 16, v32
	v_add_f32_dpp v58, v58, v58 quad_perm:[1,0,3,2] row_mask:0xf bank_mask:0xf bound_ctrl:1
	v_and_b32_e32 v45, 0xffff0000, v32
	v_lshlrev_b32_e32 v32, 16, v33
	v_add_f32_dpp v58, v58, v58 quad_perm:[2,3,0,1] row_mask:0xf bank_mask:0xf bound_ctrl:1
; __device__ __forceinline__ unsigned pk2(float lo, float hi) { return f2bf(lo) | (f2bf(hi) << 16); }
; __global__ void __launch_bounds__(NWAVES * 64, 2) hymba_fwd(Args args) {
;     ...
;             for (int j = 0; j < 4; ++j) { { const v2u wx = __builtin_nontemporal_load(xr + 64 * j); v[j] = (f32x4){bflo(wx.x), bfhi(wx.x), bflo(wx.y), bfhi(wx.y)}; } const v2u w = __builtin_nontemporal_load(mr + 64 * j); mx[j] = (f32x4){bflo(w.x), bfhi(w.x), bflo(w.y), bfhi(w.y)};
;               s += (mx[j].x * mx[j].x + mx[j].y * mx[j].y) + (mx[j].z * mx[j].z + mx[j].w * mx[j].w); }
;             const float rs = 1.0f / sqrtf(wave_sum(s) * (1.0f / DM) + EPS);
;             v2u* o8 = (v2u*)(X2B + (size_t)m * DM) + lane;
; #pragma unroll
;             for (int j = 0; j < 4; ++j) { v[j] = v[j] + mx[j] * rs * g1[j]; v2u w; w.x = pk2(v[j].x, v[j].y); w.y = pk2(v[j].z, v[j].w); o8[64 * j] = w; }
;             const f32x4 pv = __builtin_nontemporal_load((const f32x4*)prow_ptr(args, m) + lane); v2u w; w.x = pk2(pv.x, pv.y); w.y = pk2(pv.z, pv.w); *((v2u*)(PB + (size_t)m * 256) + lane) = w; }
	v_and_b32_e32 v33, 0xffff0000, v33
	v_lshlrev_b32_e32 v46, 16, v34
	v_add_f32_dpp v58, v58, v58 row_half_mirror row_mask:0xf bank_mask:0xf bound_ctrl:1
	v_and_b32_e32 v47, 0xffff0000, v34
	v_lshlrev_b32_e32 v34, 16, v35
	v_add_f32_dpp v58, v58, v58 row_mirror row_mask:0xf bank_mask:0xf bound_ctrl:1
	v_and_b32_e32 v35, 0xffff0000, v35
	s_nop 0
	v_mov_b32_dpp v56, v58 row_bcast:15 row_mask:0xa bank_mask:0xf
	v_add_f32_e32 v56, v58, v56
	s_nop 1
	v_mov_b32_dpp v57, v56 row_bcast:31 row_mask:0xc bank_mask:0xf
	v_add_f32_e32 v56, v56, v57
	s_nop 0
	v_readlane_b32 s0, v56, 63
	s_nop 1
	v_fma_f32 v56, s0, v20, v19
	v_mul_f32_e32 v57, 0x4f800000, v56
	v_cmp_gt_f32_e32 vcc, s26, v56
	s_nop 1
	v_cndmask_b32_e32 v56, v56, v57, vcc
	v_sqrt_f32_e32 v57, v56
	s_nop 0
	v_add_u32_e32 v58, -1, v57
	v_add_u32_e32 v59, 1, v57
	v_fma_f32 v60, -v58, v57, v56
	v_fma_f32 v61, -v59, v57, v56
	v_cmp_ge_f32_e64 s[0:1], 0, v60
	s_nop 1
	v_cndmask_b32_e64 v57, v57, v58, s[0:1]
	v_cmp_lt_f32_e64 s[0:1], 0, v61
	s_nop 1
	v_cndmask_b32_e64 v57, v57, v59, s[0:1]
	v_mul_f32_e32 v58, 0x37800000, v57
	v_cndmask_b32_e32 v57, v57, v58, vcc
	v_cmp_class_f32_e32 vcc, v56, v21
	s_nop 1
	v_cndmask_b32_e32 v56, v57, v56, vcc
	v_div_scale_f32 v57, s[0:1], v56, v56, 1.0
	v_rcp_f32_e32 v59, v57
	v_div_scale_f32 v58, vcc, 1.0, v56, 1.0
	v_fma_f32 v60, -v57, v59, 1.0
	v_fmac_f32_e32 v59, v60, v59
	v_mul_f32_e32 v60, v58, v59
	v_fma_f32 v61, -v57, v60, v58
	v_fmac_f32_e32 v60, v61, v59
	v_fma_f32 v57, -v57, v60, v58
	v_div_fmas_f32 v57, v57, v59, v60
	v_div_fixup_f32 v56, v57, v56, 1.0
	v_pk_mul_f32 v[48:49], v[56:57], v[48:49] op_sel_hi:[0,1]
	v_pk_mul_f32 v[24:25], v[56:57], v[24:25] op_sel_hi:[0,1]
	v_pk_mul_f32 v[50:51], v[56:57], v[50:51] op_sel_hi:[0,1]
	v_pk_mul_f32 v[36:37], v[56:57], v[36:37] op_sel_hi:[0,1]
	v_pk_mul_f32 v[52:53], v[56:57], v[52:53] op_sel_hi:[0,1]
	v_pk_mul_f32 v[38:39], v[56:57], v[38:39] op_sel_hi:[0,1]
	v_pk_mul_f32 v[54:55], v[56:57], v[54:55] op_sel_hi:[0,1]
	v_pk_mul_f32 v[26:27], v[56:57], v[26:27] op_sel_hi:[0,1]
	v_pk_fma_f32 v[24:25], v[24:25], v[2:3], v[28:29]
	v_pk_fma_f32 v[28:29], v[48:49], v[0:1], v[40:41]
	v_pk_fma_f32 v[30:31], v[36:37], v[6:7], v[30:31]
	v_pk_fma_f32 v[36:37], v[50:51], v[4:5], v[42:43]
	v_pk_fma_f32 v[32:33], v[38:39], v[10:11], v[32:33]
	v_pk_fma_f32 v[38:39], v[52:53], v[8:9], v[44:45]
	v_pk_fma_f32 v[26:27], v[26:27], v[14:15], v[34:35]
	v_pk_fma_f32 v[34:35], v[54:55], v[12:13], v[46:47]
	v_bfe_u32 v40, v28, 16, 1
	v_bfe_u32 v42, v24, 16, 1
	v_bfe_u32 v41, v29, 16, 1
	v_bfe_u32 v43, v25, 16, 1
	v_bfe_u32 v44, v36, 16, 1
	v_bfe_u32 v46, v30, 16, 1
	v_bfe_u32 v48, v38, 16, 1
	v_bfe_u32 v50, v32, 16, 1
	v_bfe_u32 v52, v34, 16, 1
	v_bfe_u32 v54, v26, 16, 1
	v_bfe_u32 v55, v27, 16, 1
	v_add3_u32 v28, v28, v40, s27
	v_add3_u32 v24, v24, v42, s27
	v_bfe_u32 v45, v37, 16, 1
	v_bfe_u32 v47, v31, 16, 1
	v_bfe_u32 v49, v39, 16, 1
	v_bfe_u32 v51, v33, 16, 1
	v_bfe_u32 v53, v35, 16, 1
	v_add3_u32 v29, v29, v41, s27
	v_add3_u32 v25, v25, v43, s27
	v_add3_u32 v36, v36, v44, s27
	v_add3_u32 v30, v30, v46, s27
	v_add3_u32 v38, v38, v48, s27
	v_add3_u32 v32, v32, v50, s27
	v_add3_u32 v34, v34, v52, s27
	v_add3_u32 v26, v26, v54, s27
	v_add3_u32 v40, v27, v55, s27
	v_lshrrev_b32_e32 v27, 16, v28
	v_lshrrev_b32_e32 v28, 16, v24
	v_add3_u32 v37, v37, v45, s27
	v_add3_u32 v31, v31, v47, s27
	v_add3_u32 v39, v39, v49, s27
	v_add3_u32 v33, v33, v51, s27
	v_add3_u32 v35, v35, v53, s27
	v_lshrrev_b32_e32 v36, 16, v36
	v_lshrrev_b32_e32 v30, 16, v30
	v_lshrrev_b32_e32 v38, 16, v38
	v_lshrrev_b32_e32 v32, 16, v32
	v_lshrrev_b32_e32 v34, 16, v34
	v_lshrrev_b32_e32 v41, 16, v26
	v_and_or_b32 v24, v29, s3, v27
	v_and_or_b32 v25, v25, s3, v28
	v_and_or_b32 v26, v37, s3, v36
	v_and_or_b32 v27, v31, s3, v30
	v_and_or_b32 v28, v39, s3, v38
	v_and_or_b32 v29, v33, s3, v32
	v_and_or_b32 v30, v35, s3, v34
	v_and_or_b32 v31, v40, s3, v41
	global_store_dwordx2 v[22:23], v[24:25], off
	global_store_dwordx2 v[22:23], v[26:27], off offset:512
	global_store_dwordx2 v[22:23], v[28:29], off offset:1024
	global_store_dwordx2 v[22:23], v[30:31], off offset:1536
	v_lshl_add_u64 v[26:27], s[12:13], 0, v[16:17]
	s_add_u32 s12, s12, s14
	s_addc_u32 s13, s13, s15
	s_add_u32 s16, s16, s18
	s_addc_u32 s17, s17, s19
	s_add_u32 s20, s20, s18
	s_addc_u32 s21, s21, s19
	s_cmp_gt_i32 s10, 0xbfff
	v_bfe_u32 v28, v100, 16, 1
	v_bfe_u32 v30, v102, 16, 1
	v_bfe_u32 v29, v101, 16, 1
	v_bfe_u32 v31, v103, 16, 1
	v_add3_u32 v22, v100, v28, s27
	v_add3_u32 v24, v102, v30, s27
	v_add3_u32 v23, v101, v29, s27
	v_add3_u32 v25, v103, v31, s27
	v_lshrrev_b32_e32 v22, 16, v22
	v_lshrrev_b32_e32 v24, 16, v24
	v_and_or_b32 v22, v23, s3, v22
	v_and_or_b32 v23, v25, s3, v24
	global_store_dwordx2 v[26:27], v[22:23], off
	s_cbranch_scc1 .LBB0_825
	s_waitcnt vmcnt(5)
	v_mov_b64_e32 v[28:29], v[104:105]
	v_mov_b64_e32 v[30:31], v[106:107]
	v_mov_b64_e32 v[32:33], v[108:109]
	v_mov_b64_e32 v[34:35], v[110:111]
	v_mov_b64_e32 v[24:25], v[112:113]
	v_mov_b64_e32 v[36:37], v[114:115]
	v_mov_b64_e32 v[38:39], v[116:117]
	v_mov_b64_e32 v[26:27], v[118:119]
	v_mov_b64_e32 v[100:101], v[120:121]
	v_mov_b64_e32 v[102:103], v[122:123]
	s_branch .LBB0_824
